# lnv inner loop: all 8 row loads prefetched at the top of each iteration (original loads become counted wait + register copies), placement preserved
# speedup vs baseline: 1.0045x; 1.0045x over previous
.LBB0_177:
	v_lshl_add_u64 v[66:67], v[34:35], 0, s[8:9]
	s_branch .Llnv_pf
.Llnv_pfd:
	v_add_co_u32_e32 v52, vcc, 0xea80000, v66
	v_lshl_add_u64 v[50:51], v[36:37], 0, s[8:9]
	s_nop 0
	v_addc_co_u32_e32 v53, vcc, 0, v67, vcc
	v_add_co_u32_e32 v56, vcc, 0xea81000, v66
	s_waitcnt vmcnt(7)
	v_mov_b64_e32 v[52:53], v[100:101]
	v_mov_b64_e32 v[54:55], v[102:103]
	v_addc_co_u32_e32 v57, vcc, 0, v67, vcc
	s_waitcnt vmcnt(6)
	v_mov_b64_e32 v[56:57], v[104:105]
	v_mov_b64_e32 v[58:59], v[106:107]
	v_lshl_add_u64 v[48:49], v[38:39], 0, s[8:9]
	s_add_u32 s8, s8, 0x8000
	s_addc_u32 s9, s9, 0
	s_cmp_eq_u32 s8, 0x20000
	v_and_b32_e32 v62, 0xffff0000, v52
	v_and_b32_e32 v68, 0xffff0000, v54
	v_lshlrev_b32_e32 v60, 16, v52
	v_lshlrev_b32_e32 v61, 16, v56
	v_and_b32_e32 v63, 0xffff0000, v56
	v_lshlrev_b32_e32 v64, 16, v53
	v_and_b32_e32 v56, 0xffff0000, v53
	v_lshlrev_b32_e32 v53, 16, v58
	v_lshlrev_b32_e32 v52, 16, v54
	v_and_b32_e32 v69, 0xffff0000, v58
	v_and_b32_e32 v58, 0xffff0000, v55
	v_mov_b32_e32 v72, v62
	v_mov_b32_e32 v73, v68
	v_lshlrev_b32_e32 v70, 16, v55
	v_mov_b32_e32 v54, v60
	v_mov_b32_e32 v55, v52
	v_pk_mul_f32 v[72:73], v[72:73], v[72:73]
	v_mov_b32_e32 v74, v56
	v_mov_b32_e32 v75, v58
	v_pk_fma_f32 v[54:55], v[54:55], v[54:55], v[72:73]
	v_mov_b32_e32 v72, v64
	v_mov_b32_e32 v73, v70
	v_pk_mul_f32 v[74:75], v[74:75], v[74:75]
	v_lshlrev_b32_e32 v65, 16, v57
	v_pk_fma_f32 v[72:73], v[72:73], v[72:73], v[74:75]
	v_and_b32_e32 v57, 0xffff0000, v57
	v_pk_add_f32 v[54:55], v[54:55], v[72:73]
	v_lshlrev_b32_e32 v71, 16, v59
	v_and_b32_e32 v59, 0xffff0000, v59
	v_add_f32_e32 v11, v54, v55
	v_pk_add_f32 v[54:55], v[60:61], v[62:63]
	v_pk_add_f32 v[72:73], v[64:65], v[56:57]
	v_pk_add_f32 v[74:75], v[70:71], v[58:59]
	v_pk_add_f32 v[54:55], v[54:55], v[72:73]
	v_pk_add_f32 v[72:73], v[52:53], v[68:69]
	v_mov_b32_e32 v68, v63
	v_mov_b32_e32 v58, v57
	v_mov_b32_e32 v52, v61
	v_pk_mul_f32 v[60:61], v[68:69], v[68:69]
	v_mov_b32_e32 v70, v65
	v_pk_mul_f32 v[56:57], v[58:59], v[58:59]
	v_pk_add_f32 v[72:73], v[72:73], v[74:75]
	v_pk_fma_f32 v[52:53], v[52:53], v[52:53], v[60:61]
	v_pk_fma_f32 v[56:57], v[70:71], v[70:71], v[56:57]
	v_pk_add_f32 v[54:55], v[54:55], v[72:73]
	v_pk_add_f32 v[52:53], v[52:53], v[56:57]
	ds_bpermute_b32 v15, v245, v11
	v_add_f32_e32 v13, v52, v53
	ds_bpermute_b32 v52, v245, v54
	ds_bpermute_b32 v53, v245, v55
	s_waitcnt lgkmcnt(0)
	v_add_f32_e32 v11, v11, v15
	ds_bpermute_b32 v15, v245, v13
	v_pk_add_f32 v[52:53], v[54:55], v[52:53]
	v_add_co_u32_e32 v54, vcc, s80, v66
	s_waitcnt lgkmcnt(0)
	v_add_f32_e32 v13, v13, v15
	v_addc_co_u32_e32 v55, vcc, 0, v67, vcc
	v_add_co_u32_e32 v58, vcc, s81, v66
	s_waitcnt vmcnt(5)
	v_mov_b64_e32 v[54:55], v[108:109]
	v_mov_b64_e32 v[56:57], v[110:111]
	v_addc_co_u32_e32 v59, vcc, 0, v67, vcc
	s_waitcnt vmcnt(4)
	v_mov_b64_e32 v[58:59], v[112:113]
	v_mov_b64_e32 v[60:61], v[114:115]
	v_and_b32_e32 v64, 0xffff0000, v54
	v_and_b32_e32 v70, 0xffff0000, v56
	v_lshlrev_b32_e32 v62, 16, v54
	v_lshlrev_b32_e32 v63, 16, v58
	v_and_b32_e32 v65, 0xffff0000, v58
	v_lshlrev_b32_e32 v68, 16, v55
	v_and_b32_e32 v58, 0xffff0000, v55
	v_lshlrev_b32_e32 v55, 16, v60
	v_lshlrev_b32_e32 v54, 16, v56
	v_and_b32_e32 v71, 0xffff0000, v60
	v_and_b32_e32 v60, 0xffff0000, v57
	v_mov_b32_e32 v74, v64
	v_mov_b32_e32 v75, v70
	v_lshlrev_b32_e32 v72, 16, v57
	v_mov_b32_e32 v56, v62
	v_mov_b32_e32 v57, v54
	v_pk_mul_f32 v[74:75], v[74:75], v[74:75]
	v_mov_b32_e32 v76, v58
	v_mov_b32_e32 v77, v60
	v_pk_fma_f32 v[56:57], v[56:57], v[56:57], v[74:75]
	v_mov_b32_e32 v74, v68
	v_mov_b32_e32 v75, v72
	v_pk_mul_f32 v[76:77], v[76:77], v[76:77]
	v_lshlrev_b32_e32 v69, 16, v59
	v_pk_fma_f32 v[74:75], v[74:75], v[74:75], v[76:77]
	v_and_b32_e32 v59, 0xffff0000, v59
	v_pk_add_f32 v[56:57], v[56:57], v[74:75]
	v_lshlrev_b32_e32 v73, 16, v61
	v_and_b32_e32 v61, 0xffff0000, v61
	v_add_f32_e32 v15, v56, v57
	v_pk_add_f32 v[56:57], v[62:63], v[64:65]
	v_pk_add_f32 v[74:75], v[68:69], v[58:59]
	v_pk_add_f32 v[76:77], v[72:73], v[60:61]
	v_pk_add_f32 v[56:57], v[56:57], v[74:75]
	v_pk_add_f32 v[74:75], v[54:55], v[70:71]
	v_mov_b32_e32 v70, v65
	v_mov_b32_e32 v60, v59
	v_mov_b32_e32 v54, v63
	v_pk_mul_f32 v[62:63], v[70:71], v[70:71]
	v_mov_b32_e32 v72, v69
	v_pk_mul_f32 v[58:59], v[60:61], v[60:61]
	v_pk_add_f32 v[74:75], v[74:75], v[76:77]
	v_pk_fma_f32 v[54:55], v[54:55], v[54:55], v[62:63]
	v_pk_fma_f32 v[58:59], v[72:73], v[72:73], v[58:59]
	v_pk_add_f32 v[56:57], v[56:57], v[74:75]
	v_pk_add_f32 v[54:55], v[54:55], v[58:59]
	ds_bpermute_b32 v21, v245, v15
	v_add_f32_e32 v19, v54, v55
	ds_bpermute_b32 v54, v245, v56
	ds_bpermute_b32 v55, v245, v57
	s_waitcnt lgkmcnt(2)
	v_add_f32_e32 v15, v15, v21
	ds_bpermute_b32 v21, v245, v19
	s_waitcnt lgkmcnt(1)
	v_pk_add_f32 v[56:57], v[56:57], v[54:55]
	v_add_co_u32_e32 v54, vcc, s82, v66
	s_waitcnt lgkmcnt(0)
	v_add_f32_e32 v19, v19, v21
	v_addc_co_u32_e32 v55, vcc, 0, v67, vcc
	s_waitcnt vmcnt(3)
	v_mov_b64_e32 v[58:59], v[116:117]
	v_mov_b64_e32 v[60:61], v[118:119]
	v_add_co_u32_e32 v54, vcc, s83, v66
	v_and_b32_e32 v68, 0xffff0000, v58
	v_addc_co_u32_e32 v55, vcc, 0, v67, vcc
	s_waitcnt vmcnt(2)
	v_mov_b64_e32 v[62:63], v[120:121]
	v_mov_b64_e32 v[64:65], v[122:123]
	v_and_b32_e32 v72, 0xffff0000, v60
	v_lshlrev_b32_e32 v54, 16, v58
	v_lshlrev_b32_e32 v70, 16, v59
	v_lshlrev_b32_e32 v58, 16, v60
	v_mov_b32_e32 v76, v68
	v_mov_b32_e32 v77, v72
	v_lshlrev_b32_e32 v74, 16, v61
	v_mov_b32_e32 v60, v54
	v_pk_mul_f32 v[76:77], v[76:77], v[76:77]
	v_lshlrev_b32_e32 v55, 16, v62
	v_and_b32_e32 v69, 0xffff0000, v62
	v_and_b32_e32 v62, 0xffff0000, v59
	v_lshlrev_b32_e32 v59, 16, v64
	v_and_b32_e32 v73, 0xffff0000, v64
	v_and_b32_e32 v64, 0xffff0000, v61
	v_mov_b32_e32 v61, v58
	v_mov_b32_e32 v78, v62
	v_mov_b32_e32 v79, v64
	v_pk_fma_f32 v[60:61], v[60:61], v[60:61], v[76:77]
	v_mov_b32_e32 v76, v70
	v_mov_b32_e32 v77, v74
	v_pk_mul_f32 v[78:79], v[78:79], v[78:79]
	v_lshlrev_b32_e32 v71, 16, v63
	v_pk_fma_f32 v[76:77], v[76:77], v[76:77], v[78:79]
	v_and_b32_e32 v63, 0xffff0000, v63
	v_pk_add_f32 v[60:61], v[60:61], v[76:77]
	v_pk_add_f32 v[76:77], v[70:71], v[62:63]
	v_add_f32_e32 v21, v60, v61
	v_pk_add_f32 v[60:61], v[54:55], v[68:69]
	v_lshlrev_b32_e32 v75, 16, v65
	v_and_b32_e32 v65, 0xffff0000, v65
	v_pk_add_f32 v[60:61], v[60:61], v[76:77]
	v_pk_add_f32 v[76:77], v[58:59], v[72:73]
	v_mov_b32_e32 v72, v69
	v_pk_add_f32 v[78:79], v[74:75], v[64:65]
	v_mov_b32_e32 v58, v55
	v_pk_mul_f32 v[54:55], v[72:73], v[72:73]
	v_mov_b32_e32 v64, v63
	v_pk_fma_f32 v[54:55], v[58:59], v[58:59], v[54:55]
	v_mov_b32_e32 v74, v71
	v_pk_mul_f32 v[58:59], v[64:65], v[64:65]
	v_pk_add_f32 v[76:77], v[76:77], v[78:79]
	v_pk_fma_f32 v[58:59], v[74:75], v[74:75], v[58:59]
	v_pk_add_f32 v[60:61], v[60:61], v[76:77]
	v_pk_add_f32 v[54:55], v[54:55], v[58:59]
	s_nop 0
	v_add_f32_e32 v23, v54, v55
	ds_bpermute_b32 v55, v245, v21
	ds_bpermute_b32 v58, v245, v23
	ds_bpermute_b32 v54, v245, v60
	s_waitcnt lgkmcnt(2)
	v_add_f32_e32 v21, v21, v55
	ds_bpermute_b32 v55, v245, v61
	s_waitcnt lgkmcnt(2)
	v_add_f32_e32 v23, v23, v58
	v_add_co_u32_e32 v58, vcc, s84, v66
	s_waitcnt lgkmcnt(0)
	v_pk_add_f32 v[54:55], v[60:61], v[54:55]
	v_addc_co_u32_e32 v59, vcc, 0, v67, vcc
	v_add_co_u32_e32 v62, vcc, s85, v66
	s_waitcnt vmcnt(1)
	v_mov_b64_e32 v[58:59], v[124:125]
	v_mov_b64_e32 v[60:61], v[126:127]
	s_nop 0
	v_addc_co_u32_e32 v63, vcc, 0, v67, vcc
	s_waitcnt vmcnt(0)
	v_mov_b64_e32 v[62:63], v[132:133]
	v_mov_b64_e32 v[64:65], v[134:135]
	v_and_b32_e32 v68, 0xffff0000, v58
	v_and_b32_e32 v72, 0xffff0000, v60
	v_lshlrev_b32_e32 v66, 16, v58
	v_lshlrev_b32_e32 v67, 16, v62
	v_and_b32_e32 v69, 0xffff0000, v62
	v_lshlrev_b32_e32 v70, 16, v59
	v_and_b32_e32 v62, 0xffff0000, v59
	v_lshlrev_b32_e32 v59, 16, v64
	v_lshlrev_b32_e32 v58, 16, v60
	v_and_b32_e32 v73, 0xffff0000, v64
	v_and_b32_e32 v64, 0xffff0000, v61
	v_mov_b32_e32 v76, v68
	v_mov_b32_e32 v77, v72
	v_lshlrev_b32_e32 v74, 16, v61
	v_mov_b32_e32 v60, v66
	v_mov_b32_e32 v61, v58
	v_pk_mul_f32 v[76:77], v[76:77], v[76:77]
	v_mov_b32_e32 v78, v62
	v_mov_b32_e32 v79, v64
	v_pk_fma_f32 v[60:61], v[60:61], v[60:61], v[76:77]
	v_mov_b32_e32 v76, v70
	v_mov_b32_e32 v77, v74
	v_pk_mul_f32 v[78:79], v[78:79], v[78:79]
	v_lshlrev_b32_e32 v71, 16, v63
	v_pk_fma_f32 v[76:77], v[76:77], v[76:77], v[78:79]
	v_and_b32_e32 v63, 0xffff0000, v63
	v_pk_add_f32 v[60:61], v[60:61], v[76:77]
	v_lshlrev_b32_e32 v75, 16, v65
	v_and_b32_e32 v65, 0xffff0000, v65
	v_add_f32_e32 v80, v60, v61
	v_pk_add_f32 v[60:61], v[66:67], v[68:69]
	v_pk_add_f32 v[76:77], v[70:71], v[62:63]
	v_pk_add_f32 v[78:79], v[74:75], v[64:65]
	v_pk_add_f32 v[60:61], v[60:61], v[76:77]
	v_pk_add_f32 v[76:77], v[58:59], v[72:73]
	v_mov_b32_e32 v72, v69
	v_mov_b32_e32 v64, v63
	v_mov_b32_e32 v58, v67
	v_pk_mul_f32 v[66:67], v[72:73], v[72:73]
	v_mov_b32_e32 v74, v71
	v_pk_mul_f32 v[62:63], v[64:65], v[64:65]
	v_pk_fma_f32 v[58:59], v[58:59], v[58:59], v[66:67]
	v_pk_fma_f32 v[62:63], v[74:75], v[74:75], v[62:63]
	v_pk_add_f32 v[76:77], v[76:77], v[78:79]
	v_pk_add_f32 v[58:59], v[58:59], v[62:63]
	v_pk_add_f32 v[60:61], v[60:61], v[76:77]
	v_add_f32_e32 v62, v58, v59
	ds_bpermute_b32 v59, v245, v80
	ds_bpermute_b32 v58, v245, v60
	ds_bpermute_b32 v72, v246, v52
	ds_bpermute_b32 v73, v246, v53
	ds_bpermute_b32 v74, v246, v56
	s_waitcnt lgkmcnt(4)
	v_add_f32_e32 v63, v80, v59
	ds_bpermute_b32 v59, v245, v61
	ds_bpermute_b32 v65, v246, v63
	ds_bpermute_b32 v75, v246, v57
	s_waitcnt lgkmcnt(4)
	v_pk_add_f32 v[52:53], v[52:53], v[72:73]
	ds_bpermute_b32 v72, v247, v52
	s_waitcnt lgkmcnt(3)
	v_pk_add_f32 v[58:59], v[60:61], v[58:59]
	ds_bpermute_b32 v60, v245, v62
	ds_bpermute_b32 v61, v246, v21
	s_waitcnt lgkmcnt(4)
	v_add_f32_e32 v65, v63, v65
	s_waitcnt lgkmcnt(3)
	v_pk_add_f32 v[56:57], v[56:57], v[74:75]
	ds_bpermute_b32 v73, v247, v53
	s_waitcnt lgkmcnt(2)
	v_add_f32_e32 v64, v62, v60
	ds_bpermute_b32 v60, v246, v11
	ds_bpermute_b32 v66, v246, v64
	s_waitcnt lgkmcnt(3)
	v_add_f32_e32 v21, v21, v61
	ds_bpermute_b32 v62, v246, v23
	ds_bpermute_b32 v74, v247, v56
	s_waitcnt lgkmcnt(3)
	v_add_f32_e32 v11, v11, v60
	ds_bpermute_b32 v60, v246, v13
	s_waitcnt lgkmcnt(3)
	v_add_f32_e32 v64, v64, v66
	ds_bpermute_b32 v66, v247, v11
	s_waitcnt lgkmcnt(3)
	v_add_f32_e32 v23, v23, v62
	ds_bpermute_b32 v75, v247, v57
	s_waitcnt lgkmcnt(2)
	v_add_f32_e32 v13, v13, v60
	ds_bpermute_b32 v60, v246, v15
	s_waitcnt lgkmcnt(2)
	v_add_f32_e32 v11, v11, v66
	ds_bpermute_b32 v66, v247, v13
	v_pk_add_f32 v[52:53], v[52:53], v[72:73]
	s_waitcnt lgkmcnt(2)
	v_pk_add_f32 v[56:57], v[56:57], v[74:75]
	s_waitcnt lgkmcnt(1)
	v_add_f32_e32 v15, v15, v60
	ds_bpermute_b32 v60, v246, v19
	s_waitcnt lgkmcnt(1)
	v_add_f32_e32 v13, v13, v66
	ds_bpermute_b32 v66, v247, v15
	ds_bpermute_b32 v72, v248, v52
	ds_bpermute_b32 v73, v248, v53
	s_waitcnt lgkmcnt(3)
	v_add_f32_e32 v19, v19, v60
	ds_bpermute_b32 v74, v248, v56
	s_waitcnt lgkmcnt(3)
	v_add_f32_e32 v15, v15, v66
	ds_bpermute_b32 v66, v247, v19
	ds_bpermute_b32 v75, v248, v57
	s_waitcnt lgkmcnt(3)
	v_pk_add_f32 v[52:53], v[52:53], v[72:73]
	ds_bpermute_b32 v72, v249, v52
	ds_bpermute_b32 v73, v249, v53
	s_waitcnt lgkmcnt(3)
	v_add_f32_e32 v19, v19, v66
	ds_bpermute_b32 v66, v247, v21
	s_waitcnt lgkmcnt(3)
	v_pk_add_f32 v[56:57], v[56:57], v[74:75]
	ds_bpermute_b32 v74, v249, v56
	ds_bpermute_b32 v75, v249, v57
	s_waitcnt lgkmcnt(3)
	v_pk_add_f32 v[52:53], v[52:53], v[72:73]
	s_waitcnt lgkmcnt(2)
	v_add_f32_e32 v21, v21, v66
	ds_bpermute_b32 v66, v247, v23
	ds_bpermute_b32 v72, v250, v52
	s_waitcnt lgkmcnt(2)
	v_pk_add_f32 v[56:57], v[56:57], v[74:75]
	ds_bpermute_b32 v73, v250, v53
	ds_bpermute_b32 v74, v250, v56
	s_waitcnt lgkmcnt(3)
	v_add_f32_e32 v23, v23, v66
	ds_bpermute_b32 v66, v247, v65
	ds_bpermute_b32 v75, v250, v57
	s_waitcnt lgkmcnt(3)
	v_pk_add_f32 v[52:53], v[52:53], v[72:73]
	ds_bpermute_b32 v60, v246, v54
	ds_bpermute_b32 v61, v246, v55
	s_waitcnt lgkmcnt(3)
	v_add_f32_e32 v65, v65, v66
	ds_bpermute_b32 v66, v247, v64
	s_waitcnt lgkmcnt(3)
	v_pk_add_f32 v[56:57], v[56:57], v[74:75]
	v_pk_mul_f32 v[74:75], v[52:53], s[26:27] op_sel_hi:[1,0]
	v_pk_mul_f32 v[72:73], v[56:57], s[26:27] op_sel_hi:[1,0]
	v_mov_b32_e32 v83, v74
	s_waitcnt lgkmcnt(0)
	v_add_f32_e32 v64, v64, v66
	ds_bpermute_b32 v66, v248, v11
	v_mov_b32_e32 v143, v74
	v_mov_b32_e32 v81, v75
	v_mov_b32_e32 v79, v72
	v_mov_b32_e32 v77, v73
	s_waitcnt lgkmcnt(0)
	v_add_f32_e32 v11, v11, v66
	ds_bpermute_b32 v66, v248, v13
	ds_bpermute_b32 v62, v246, v58
	ds_bpermute_b32 v63, v246, v59
	v_pk_add_f32 v[54:55], v[54:55], v[60:61]
	ds_bpermute_b32 v60, v247, v54
	s_waitcnt lgkmcnt(3)
	v_add_f32_e32 v13, v13, v66
	ds_bpermute_b32 v66, v248, v15
	s_waitcnt lgkmcnt(2)
	v_pk_add_f32 v[58:59], v[58:59], v[62:63]
	ds_bpermute_b32 v61, v247, v55
	ds_bpermute_b32 v62, v247, v58
	ds_bpermute_b32 v63, v247, v59
	s_waitcnt lgkmcnt(3)
	v_add_f32_e32 v15, v15, v66
	ds_bpermute_b32 v66, v248, v19
	s_waitcnt lgkmcnt(3)
	v_pk_add_f32 v[54:55], v[54:55], v[60:61]
	ds_bpermute_b32 v60, v248, v54
	s_waitcnt lgkmcnt(2)
	v_pk_add_f32 v[58:59], v[58:59], v[62:63]
	ds_bpermute_b32 v61, v248, v55
	s_waitcnt lgkmcnt(2)
	v_add_f32_e32 v19, v19, v66
	ds_bpermute_b32 v66, v248, v21
	ds_bpermute_b32 v62, v248, v58
	ds_bpermute_b32 v63, v248, v59
	s_waitcnt lgkmcnt(3)
	v_pk_add_f32 v[54:55], v[54:55], v[60:61]
	ds_bpermute_b32 v60, v249, v54
	s_waitcnt lgkmcnt(3)
	v_add_f32_e32 v21, v21, v66
	ds_bpermute_b32 v66, v248, v23
	s_waitcnt lgkmcnt(2)
	v_pk_add_f32 v[58:59], v[58:59], v[62:63]
	ds_bpermute_b32 v61, v249, v55
	ds_bpermute_b32 v62, v249, v58
	ds_bpermute_b32 v63, v249, v59
	s_waitcnt lgkmcnt(3)
	v_add_f32_e32 v23, v23, v66
	ds_bpermute_b32 v66, v248, v65
	s_waitcnt lgkmcnt(3)
	v_pk_add_f32 v[54:55], v[54:55], v[60:61]
	ds_bpermute_b32 v60, v250, v54
	s_waitcnt lgkmcnt(2)
	v_pk_add_f32 v[58:59], v[58:59], v[62:63]
	ds_bpermute_b32 v61, v250, v55
	s_waitcnt lgkmcnt(2)
	v_add_f32_e32 v65, v65, v66
	ds_bpermute_b32 v66, v248, v64
	ds_bpermute_b32 v62, v250, v58
	ds_bpermute_b32 v63, v250, v59
	s_waitcnt lgkmcnt(3)
	v_pk_add_f32 v[54:55], v[54:55], v[60:61]
	s_waitcnt lgkmcnt(2)
	v_add_f32_e32 v64, v64, v66
	ds_bpermute_b32 v66, v249, v11
	s_waitcnt lgkmcnt(1)
	v_pk_add_f32 v[58:59], v[58:59], v[62:63]
	v_pk_mul_f32 v[62:63], v[54:55], s[26:27] op_sel_hi:[1,0]
	v_pk_mul_f32 v[60:61], v[58:59], s[26:27] op_sel_hi:[1,0]
	v_mov_b32_e32 v71, v62
	s_waitcnt lgkmcnt(0)
	v_add_f32_e32 v11, v11, v66
	ds_bpermute_b32 v66, v249, v13
	v_mov_b32_e32 v69, v63
	v_mov_b32_e32 v67, v60
	s_waitcnt lgkmcnt(0)
	v_add_f32_e32 v13, v13, v66
	ds_bpermute_b32 v66, v249, v15
	s_waitcnt lgkmcnt(0)
	v_add_f32_e32 v15, v15, v66
	ds_bpermute_b32 v66, v249, v19
	s_waitcnt lgkmcnt(0)
	v_add_f32_e32 v19, v19, v66
	ds_bpermute_b32 v66, v249, v21
	s_waitcnt lgkmcnt(0)
	v_add_f32_e32 v21, v21, v66
	ds_bpermute_b32 v66, v249, v23
	s_waitcnt lgkmcnt(0)
	v_add_f32_e32 v23, v23, v66
	ds_bpermute_b32 v66, v249, v65
	s_waitcnt lgkmcnt(0)
	v_add_f32_e32 v65, v65, v66
	ds_bpermute_b32 v66, v249, v64
	s_waitcnt lgkmcnt(0)
	v_add_f32_e32 v64, v64, v66
	ds_bpermute_b32 v66, v250, v11
	s_waitcnt lgkmcnt(0)
	v_add_f32_e32 v82, v11, v66
	ds_bpermute_b32 v11, v250, v13
	v_pk_mul_f32 v[82:83], v[82:83], v[142:143]
	v_mov_b32_e32 v143, v75
	s_waitcnt lgkmcnt(0)
	v_add_f32_e32 v80, v13, v11
	ds_bpermute_b32 v11, v250, v15
	v_sub_f32_e32 v13, v82, v83
	v_pk_mul_f32 v[80:81], v[80:81], v[142:143]
	v_mov_b32_e32 v143, v72
	v_max_f32_e32 v74, 0, v13
	s_waitcnt lgkmcnt(0)
	v_add_f32_e32 v78, v15, v11
	ds_bpermute_b32 v11, v250, v19
	v_sub_f32_e32 v13, v80, v81
	v_pk_mul_f32 v[78:79], v[78:79], v[142:143]
	v_mov_b32_e32 v143, v73
	v_max_f32_e32 v75, 0, v13
	s_waitcnt lgkmcnt(0)
	v_add_f32_e32 v76, v19, v11
	v_sub_f32_e32 v13, v78, v79
	v_pk_mul_f32 v[76:77], v[76:77], v[142:143]
	v_max_f32_e32 v72, 0, v13
	v_sub_f32_e32 v13, v76, v77
	v_pk_add_f32 v[74:75], v[74:75], s[22:23] op_sel_hi:[1,0]
	v_max_f32_e32 v73, 0, v13
	v_mul_f32_e32 v13, 0x4b800000, v74
	v_cmp_gt_f32_e64 s[44:45], s86, v74
	v_cmp_gt_f32_e64 s[42:43], s86, v75
	v_pk_add_f32 v[72:73], v[72:73], s[22:23] op_sel_hi:[1,0]
	v_cndmask_b32_e64 v13, v74, v13, s[44:45]
	v_rsq_f32_e32 v74, v13
	v_mul_f32_e32 v13, 0x4b800000, v75
	v_cndmask_b32_e64 v13, v75, v13, s[42:43]
	v_cmp_gt_f32_e64 s[40:41], s86, v72
	v_rsq_f32_e32 v75, v13
	v_mul_f32_e32 v13, 0x4b800000, v72
	v_cndmask_b32_e64 v13, v72, v13, s[40:41]
	v_cmp_gt_f32_e32 vcc, s86, v73
	v_rsq_f32_e32 v72, v13
	v_mul_f32_e32 v13, 0x4b800000, v73
	v_cndmask_b32_e32 v13, v73, v13, vcc
	v_rsq_f32_e32 v73, v13
	v_pk_mul_f32 v[76:77], v[74:75], s[10:11] op_sel_hi:[1,0]
	ds_bpermute_b32 v11, v250, v21
	v_cndmask_b32_e64 v74, v74, v76, s[44:45]
	v_pk_mul_f32 v[78:79], v[72:73], s[10:11] op_sel_hi:[1,0]
	v_cndmask_b32_e64 v75, v75, v77, s[42:43]
	v_cndmask_b32_e32 v73, v73, v79, vcc
	v_add_co_u32_e32 v76, vcc, s80, v50
	s_waitcnt lgkmcnt(0)
	v_add_f32_e32 v70, v21, v11
	v_addc_co_u32_e32 v77, vcc, 0, v51, vcc
	global_load_ushort v13, v[76:77], off offset:1024
	v_add_co_u32_e32 v76, vcc, s81, v50
	v_cndmask_b32_e64 v72, v72, v78, s[40:41]
	s_nop 0
	v_addc_co_u32_e32 v77, vcc, 0, v51, vcc
	global_load_ushort v15, v[76:77], off offset:1024
	v_add_co_u32_e32 v76, vcc, s91, v50
	ds_bpermute_b32 v11, v250, v23
	s_nop 0
	v_addc_co_u32_e32 v77, vcc, 0, v51, vcc
	global_load_ushort v19, v[76:77], off offset:1024
	v_add_co_u32_e32 v76, vcc, s11, v50
	s_waitcnt lgkmcnt(0)
	v_add_f32_e32 v68, v23, v11
	v_addc_co_u32_e32 v77, vcc, 0, v51, vcc
	global_load_ushort v21, v[76:77], off offset:1024
	v_add_co_u32_e32 v80, vcc, s80, v48
	ds_bpermute_b32 v11, v250, v65
	s_nop 0
	v_addc_co_u32_e32 v81, vcc, 0, v49, vcc
	v_mov_b32_e32 v143, v62
	v_pk_mul_f32 v[70:71], v[70:71], v[142:143]
	s_waitcnt lgkmcnt(0)
	v_add_f32_e32 v66, v65, v11
	ds_bpermute_b32 v11, v250, v64
	v_mov_b32_e32 v143, v63
	v_pk_mul_f32 v[68:69], v[68:69], v[142:143]
	v_mov_b32_e32 v143, v60
	v_pk_mul_f32 v[66:67], v[66:67], v[142:143]
	s_waitcnt lgkmcnt(0)
	v_add_f32_e32 v64, v64, v11
	v_mov_b32_e32 v65, v61
	v_mov_b32_e32 v143, v61
	v_pk_mul_f32 v[64:65], v[64:65], v[142:143]
	v_add_u32_e32 v11, 0x4200, v9
	s_waitcnt vmcnt(3)
	v_lshlrev_b32_e32 v78, 16, v13
	global_load_ushort v13, v[80:81], off offset:1024
	v_add_co_u32_e32 v80, vcc, s81, v48
	s_waitcnt vmcnt(3)
	v_lshlrev_b32_e32 v79, 16, v15
	v_addc_co_u32_e32 v81, vcc, 0, v49, vcc
	global_load_ushort v15, v[80:81], off offset:1024
	v_add_co_u32_e32 v80, vcc, s91, v48
	s_waitcnt vmcnt(3)
	v_lshlrev_b32_e32 v76, 16, v19
	v_addc_co_u32_e32 v81, vcc, 0, v49, vcc
	global_load_ushort v19, v[80:81], off offset:1024
	v_add_co_u32_e32 v80, vcc, s11, v48
	s_waitcnt vmcnt(3)
	v_lshlrev_b32_e32 v77, 16, v21
	v_addc_co_u32_e32 v81, vcc, 0, v49, vcc
	global_load_ushort v21, v[80:81], off offset:1024
	v_pk_fma_f32 v[78:79], v[56:57], s[26:27], v[78:79] op_sel_hi:[1,0,1] neg_lo:[1,0,0] neg_hi:[1,0,0]
	v_pk_fma_f32 v[76:77], v[52:53], s[26:27], v[76:77] op_sel_hi:[1,0,1] neg_lo:[1,0,0] neg_hi:[1,0,0]
	v_pk_mul_f32 v[78:79], v[78:79], v[72:73]
	v_pk_mul_f32 v[76:77], v[76:77], v[74:75]
	v_pk_fma_f32 v[78:79], v[42:43], v[78:79], v[40:41]
	v_pk_fma_f32 v[76:77], v[28:29], v[76:77], v[24:25]
	s_waitcnt vmcnt(3)
	v_lshlrev_b32_e32 v82, 16, v13
	v_sub_f32_e32 v13, v70, v71
	v_max_f32_e32 v62, 0, v13
	v_sub_f32_e32 v13, v68, v69
	v_max_f32_e32 v63, 0, v13
	v_sub_f32_e32 v13, v66, v67
	v_max_f32_e32 v60, 0, v13
	v_sub_f32_e32 v13, v64, v65
	v_pk_add_f32 v[62:63], v[62:63], s[22:23] op_sel_hi:[1,0]
	v_max_f32_e32 v61, 0, v13
	v_mul_f32_e32 v13, 0x4b800000, v62
	v_cmp_gt_f32_e64 s[44:45], s86, v62
	v_cmp_gt_f32_e64 s[42:43], s86, v63
	v_pk_add_f32 v[60:61], v[60:61], s[22:23] op_sel_hi:[1,0]
	v_cndmask_b32_e64 v13, v62, v13, s[44:45]
	v_rsq_f32_e32 v62, v13
	v_mul_f32_e32 v13, 0x4b800000, v63
	v_cndmask_b32_e64 v13, v63, v13, s[42:43]
	v_cmp_gt_f32_e64 s[40:41], s86, v60
	v_rsq_f32_e32 v63, v13
	v_mul_f32_e32 v13, 0x4b800000, v60
	v_cndmask_b32_e64 v13, v60, v13, s[40:41]
	v_cmp_gt_f32_e32 vcc, s86, v61
	v_rsq_f32_e32 v60, v13
	v_mul_f32_e32 v13, 0x4b800000, v61
	v_cndmask_b32_e32 v13, v61, v13, vcc
	v_rsq_f32_e32 v61, v13
	v_pk_mul_f32 v[64:65], v[62:63], s[10:11] op_sel_hi:[1,0]
	s_waitcnt vmcnt(2)
	v_lshlrev_b32_e32 v83, 16, v15
	v_cndmask_b32_e64 v62, v62, v64, s[44:45]
	v_pk_mul_f32 v[66:67], v[60:61], s[10:11] op_sel_hi:[1,0]
	v_cndmask_b32_e64 v63, v63, v65, s[42:43]
	v_cndmask_b32_e32 v61, v61, v67, vcc
	v_add_co_u32_e32 v64, vcc, s84, v50
	v_cndmask_b32_e64 v60, v60, v66, s[40:41]
	s_nop 0
	v_addc_co_u32_e32 v65, vcc, 0, v51, vcc
	global_load_ushort v13, v[64:65], off offset:1024
	v_add_co_u32_e32 v64, vcc, s85, v50
	s_waitcnt vmcnt(1)
	v_lshlrev_b32_e32 v81, 16, v21
	v_addc_co_u32_e32 v65, vcc, 0, v51, vcc
	global_load_ushort v15, v[64:65], off offset:1024
	v_add_co_u32_e32 v64, vcc, s82, v50
	v_lshlrev_b32_e32 v80, 16, v19
	s_nop 0
	v_addc_co_u32_e32 v65, vcc, 0, v51, vcc
	v_add_co_u32_e32 v50, vcc, s83, v50
	global_load_ushort v19, v[64:65], off offset:1024
	s_nop 0
	v_addc_co_u32_e32 v51, vcc, 0, v51, vcc
	global_load_ushort v21, v[50:51], off offset:1024
	v_add_co_u32_e32 v66, vcc, s84, v48
	v_pk_fma_f32 v[56:57], v[56:57], s[26:27], v[82:83] op_sel_hi:[1,0,1] neg_lo:[1,0,0] neg_hi:[1,0,0]
	s_nop 0
	v_addc_co_u32_e32 v67, vcc, 0, v49, vcc
	v_pk_fma_f32 v[52:53], v[52:53], s[26:27], v[80:81] op_sel_hi:[1,0,1] neg_lo:[1,0,0] neg_hi:[1,0,0]
	v_pk_mul_f32 v[56:57], v[56:57], v[72:73]
	v_pk_mul_f32 v[52:53], v[52:53], v[74:75]
	v_pk_fma_f32 v[56:57], v[46:47], v[56:57], v[44:45]
	v_pk_fma_f32 v[52:53], v[26:27], v[52:53], v[32:33]
	s_waitcnt vmcnt(3)
	v_lshlrev_b32_e32 v64, 16, v13
	global_load_ushort v13, v[66:67], off offset:1024
	v_add_co_u32_e32 v66, vcc, s85, v48
	s_waitcnt vmcnt(3)
	v_lshlrev_b32_e32 v65, 16, v15
	v_addc_co_u32_e32 v67, vcc, 0, v49, vcc
	global_load_ushort v15, v[66:67], off offset:1024
	v_add_co_u32_e32 v66, vcc, s82, v48
	v_pk_fma_f32 v[64:65], v[58:59], s[26:27], v[64:65] op_sel_hi:[1,0,1] neg_lo:[1,0,0] neg_hi:[1,0,0]
	s_nop 0
	v_addc_co_u32_e32 v67, vcc, 0, v49, vcc
	v_add_co_u32_e32 v48, vcc, s83, v48
	s_waitcnt vmcnt(2)
	v_lshlrev_b32_e32 v51, 16, v21
	v_addc_co_u32_e32 v49, vcc, 0, v49, vcc
	v_lshlrev_b32_e32 v50, 16, v19
	global_load_ushort v19, v[66:67], off offset:1024
	global_load_ushort v21, v[48:49], off offset:1024
	v_pk_fma_f32 v[50:51], v[54:55], s[26:27], v[50:51] op_sel_hi:[1,0,1] neg_lo:[1,0,0] neg_hi:[1,0,0]
	v_pk_mul_f32 v[64:65], v[64:65], v[60:61]
	v_pk_mul_f32 v[50:51], v[50:51], v[62:63]
	v_pk_fma_f32 v[64:65], v[42:43], v[64:65], v[40:41]
	v_pk_fma_f32 v[50:51], v[28:29], v[50:51], v[24:25]
	v_cvt_pk_bf16_f32 v65, v64, v65
	v_cvt_pk_bf16_f32 v64, v50, v51
	v_cvt_pk_bf16_f32 v51, v78, v79
	v_cvt_pk_bf16_f32 v50, v76, v77
	ds_write2_b64 v9, v[50:51], v[64:65] offset1:1
	v_add_u32_e32 v9, 16, v9
	s_waitcnt vmcnt(3)
	v_lshlrev_b32_e32 v50, 16, v13
	s_waitcnt vmcnt(2)
	v_lshlrev_b32_e32 v51, 16, v15
	v_pk_fma_f32 v[50:51], v[58:59], s[26:27], v[50:51] op_sel_hi:[1,0,1] neg_lo:[1,0,0] neg_hi:[1,0,0]
	s_waitcnt vmcnt(1)
	v_lshlrev_b32_e32 v48, 16, v19
	s_waitcnt vmcnt(0)
	v_lshlrev_b32_e32 v49, 16, v21
	v_pk_fma_f32 v[48:49], v[54:55], s[26:27], v[48:49] op_sel_hi:[1,0,1] neg_lo:[1,0,0] neg_hi:[1,0,0]
	v_pk_mul_f32 v[50:51], v[50:51], v[60:61]
	v_pk_mul_f32 v[48:49], v[48:49], v[62:63]
	v_pk_fma_f32 v[50:51], v[46:47], v[50:51], v[44:45]
	v_pk_fma_f32 v[48:49], v[26:27], v[48:49], v[32:33]
	v_cvt_pk_bf16_f32 v51, v50, v51
	v_cvt_pk_bf16_f32 v50, v48, v49
	v_cvt_pk_bf16_f32 v49, v56, v57
	v_cvt_pk_bf16_f32 v48, v52, v53
	ds_write2_b64 v11, v[48:49], v[50:51] offset1:1
	s_cbranch_scc0 .LBB0_177
	v_mul_u32_u24_e32 v128, 0x180, v7
	v_lshl_add_u64 v[24:25], v[128:129], 0, v[30:31]
	v_lshlrev_b64 v[24:25], 15, v[24:25]
	s_waitcnt lgkmcnt(0)
	s_barrier
	v_lshl_add_u64 v[28:29], v[0:1], 0, v[24:25]
	ds_read2_b64 v[24:27], v90 offset1:1
	v_mov_b32_e32 v7, v129
	v_lshl_add_u64 v[30:31], v[28:29], 0, v[6:7]
	v_mov_b32_e32 v9, v129
	v_mov_b32_e32 v11, v129
	s_waitcnt lgkmcnt(0)
	global_store_dwordx4 v[30:31], v[24:27], off
	ds_read2_b64 v[24:27], v91 offset1:1
	v_lshl_add_u64 v[30:31], v[28:29], 0, v[8:9]
	v_mov_b32_e32 v13, v129
	v_mov_b32_e32 v15, v129
	v_mov_b32_e32 v19, v129
	s_waitcnt lgkmcnt(0)
	global_store_dwordx4 v[30:31], v[24:27], off
	ds_read2_b64 v[24:27], v92 offset1:1
	v_lshl_add_u64 v[30:31], v[28:29], 0, v[10:11]
	v_mov_b32_e32 v21, v129
	v_add_u32_e32 v98, s23, v98
	s_movk_i32 s0, 0x5ff
	s_waitcnt lgkmcnt(0)
	global_store_dwordx4 v[30:31], v[24:27], off
	ds_read2_b64 v[24:27], v93 offset1:1
	v_lshl_add_u64 v[30:31], v[28:29], 0, v[12:13]
	v_mov_b32_e32 v23, v129
	v_cmp_lt_i32_e32 vcc, s0, v98
	v_subrev_u16_e32 v88, s23, v88
	s_waitcnt lgkmcnt(0)
	global_store_dwordx4 v[30:31], v[24:27], off
	ds_read2_b64 v[24:27], v94 offset1:1
	v_lshl_add_u64 v[30:31], v[28:29], 0, v[14:15]
	s_or_b64 s[12:13], vcc, s[12:13]
	s_waitcnt lgkmcnt(0)
	global_store_dwordx4 v[30:31], v[24:27], off
	ds_read2_b64 v[24:27], v95 offset1:1
	v_lshl_add_u64 v[30:31], v[28:29], 0, v[18:19]
	s_waitcnt lgkmcnt(0)
	global_store_dwordx4 v[30:31], v[24:27], off
	ds_read2_b64 v[24:27], v96 offset1:1
	v_lshl_add_u64 v[30:31], v[28:29], 0, v[20:21]
	v_lshl_add_u64 v[28:29], v[28:29], 0, v[22:23]
	s_waitcnt lgkmcnt(0)
	global_store_dwordx4 v[30:31], v[24:27], off
	ds_read2_b64 v[24:27], v97 offset1:1
	s_waitcnt lgkmcnt(0)
	global_store_dwordx4 v[28:29], v[24:27], off
	s_barrier
	s_andn2_b64 exec, exec, s[12:13]
	s_cbranch_execnz .LBB0_176
	s_or_b64 exec, exec, s[12:13]

.Llnv_pf:
	v_add_co_u32_e32 v136, vcc, 0xea80000, v66
	s_nop 0
	v_addc_co_u32_e32 v137, vcc, 0, v67, vcc
	global_load_dwordx4 v[100:103], v[136:137], off offset:1024
	v_add_co_u32_e32 v136, vcc, 0xea81000, v66
	s_nop 0
	v_addc_co_u32_e32 v137, vcc, 0, v67, vcc
	global_load_dwordx4 v[104:107], v[136:137], off offset:1024
	v_add_co_u32_e32 v136, vcc, s80, v66
	s_nop 0
	v_addc_co_u32_e32 v137, vcc, 0, v67, vcc
	global_load_dwordx4 v[108:111], v[136:137], off offset:1024
	v_add_co_u32_e32 v136, vcc, s81, v66
	s_nop 0
	v_addc_co_u32_e32 v137, vcc, 0, v67, vcc
	global_load_dwordx4 v[112:115], v[136:137], off offset:1024
	v_add_co_u32_e32 v136, vcc, s82, v66
	s_nop 0
	v_addc_co_u32_e32 v137, vcc, 0, v67, vcc
	global_load_dwordx4 v[116:119], v[136:137], off offset:1024
	v_add_co_u32_e32 v136, vcc, s83, v66
	s_nop 0
	v_addc_co_u32_e32 v137, vcc, 0, v67, vcc
	global_load_dwordx4 v[120:123], v[136:137], off offset:1024
	v_add_co_u32_e32 v136, vcc, s84, v66
	s_nop 0
	v_addc_co_u32_e32 v137, vcc, 0, v67, vcc
	global_load_dwordx4 v[124:127], v[136:137], off offset:1024
	v_add_co_u32_e32 v136, vcc, s85, v66
	s_nop 0
	v_addc_co_u32_e32 v137, vcc, 0, v67, vcc
	global_load_dwordx4 v[132:135], v[136:137], off offset:1024
	s_branch .Llnv_pfd

.Lnm_pro:
	v_lshl_add_u64 v[112:113], s[88:89], 0, v[36:37]
	v_lshl_add_u64 v[114:115], s[88:89], 0, v[58:59]
	v_add_co_u32_e32 v112, vcc, 0x8a80000, v112
	s_nop 0
	v_addc_co_u32_e32 v113, vcc, 0, v113, vcc
	global_load_dwordx4 v[0:3], v[114:115], off
	global_load_dwordx4 v[4:7], v[114:115], off offset:1024
	global_load_dwordx4 v[8:11], v[112:113], off
	global_load_dwordx4 v[12:15], v[112:113], off offset:1024
	s_branch .LBB0_318
	s_nop 0
	s_nop 0
	s_nop 0
	s_nop 0
	s_nop 0
	s_nop 0
	s_nop 0
	s_nop 0
	s_nop 0
	s_nop 0
	s_nop 0
	s_nop 0
	s_nop 0
	s_nop 0
	s_nop 0
	s_nop 0
	s_nop 0
	s_nop 0
	s_nop 0
	s_nop 0
	s_nop 0
	s_nop 0
	s_nop 0
	s_nop 0
	s_nop 0
	s_nop 0
	s_nop 0
	s_nop 0
	s_nop 0
	s_nop 0
	s_nop 0
	s_nop 0
	s_nop 0
	s_nop 0
	s_nop 0
	s_nop 0
	s_nop 0
	s_nop 0
	s_nop 0
	s_nop 0
	s_nop 0
	s_nop 0
	s_nop 0
	s_nop 0
	s_nop 0
	s_nop 0
	s_nop 0
	s_nop 0
	s_nop 0
	s_nop 0
	s_nop 0
	s_nop 0
	s_nop 0
	s_nop 0
	s_nop 0
	s_nop 0
	s_nop 0
	s_nop 0
	s_nop 0
	s_nop 0
	s_nop 0
	s_nop 0
	s_nop 0
	s_nop 0
	s_nop 0
	s_nop 0
	s_nop 0
	s_nop 0
	s_nop 0
	s_nop 0
	s_nop 0
	s_nop 0
	s_nop 0
	s_nop 0
	s_nop 0
	s_nop 0
	s_nop 0
	s_nop 0
	s_nop 0
	s_nop 0
	s_nop 0
	s_nop 0
	s_nop 0
	s_nop 0
	s_nop 0
	s_nop 0
	s_nop 0
	s_nop 0
	s_nop 0
	s_nop 0
	s_nop 0
	s_nop 0
	s_nop 0
	s_nop 0
	s_nop 0
	s_nop 0
	s_nop 0
	s_nop 0
	s_nop 0
	s_nop 0
	s_nop 0
	s_nop 0
	s_nop 0
	s_nop 0
	s_nop 0
	s_nop 0
	s_nop 0
	s_nop 0
	s_nop 0
	s_nop 0
	s_nop 0
	s_nop 0
	s_nop 0
	s_nop 0
	s_nop 0
	s_nop 0
	s_nop 0
	s_nop 0
	s_nop 0
	s_nop 0
	s_nop 0
	s_nop 0
	s_nop 0
	s_nop 0
	s_nop 0
	s_nop 0
	s_nop 0
	s_nop 0
	s_nop 0
	s_nop 0
	s_nop 0
	s_nop 0
	s_nop 0
	s_nop 0
	s_nop 0
	s_nop 0
	s_nop 0
	s_nop 0
	s_nop 0
	s_nop 0
	s_nop 0
	s_nop 0
	s_nop 0
	s_nop 0
	s_nop 0
	s_nop 0
	s_nop 0
	s_nop 0
	s_nop 0
	s_nop 0
	s_nop 0
	s_nop 0
	s_nop 0
	s_nop 0
	s_nop 0
	s_nop 0
	s_nop 0
	s_nop 0
	s_nop 0
	s_nop 0
	s_nop 0
	s_nop 0
	s_nop 0
	s_nop 0
	s_nop 0
	s_nop 0
	s_nop 0
	s_nop 0
	s_nop 0
	s_nop 0
	s_nop 0
	s_nop 0
	s_nop 0
	s_nop 0
	s_nop 0
	s_nop 0
	s_nop 0
	s_nop 0
	s_nop 0
	s_nop 0
	s_nop 0
	s_nop 0
	s_nop 0
	s_nop 0
	s_nop 0
	s_nop 0
	s_nop 0
	s_nop 0
	s_nop 0
	s_nop 0
	s_nop 0
	s_nop 0
	s_nop 0
	s_nop 0
	s_nop 0
	s_nop 0
	s_nop 0
	s_nop 0
	s_nop 0
	s_nop 0
	s_nop 0
	s_nop 0
	s_nop 0
	s_nop 0
	s_nop 0
	s_nop 0
	s_nop 0
	s_nop 0
	s_nop 0
	s_nop 0
	s_nop 0
	s_nop 0
	s_nop 0
	s_nop 0
	s_nop 0
	s_nop 0
	s_nop 0
	s_nop 0
	s_nop 0
	s_nop 0
	s_nop 0
	s_nop 0
	s_nop 0
	s_nop 0
	s_nop 0
	s_nop 0
	s_nop 0
	s_nop 0
	s_nop 0
	s_nop 0
	s_nop 0
	s_nop 0
	s_nop 0
	s_nop 0
	s_nop 0
	s_nop 0
	s_nop 0
	s_nop 0
	s_nop 0
	s_nop 0
	s_nop 0
	s_nop 0
	s_nop 0
	s_nop 0
	s_nop 0
	s_nop 0
	s_nop 0
	s_nop 0
	s_nop 0
	s_nop 0
	s_nop 0
	s_nop 0
	s_nop 0
	s_nop 0
	s_nop 0
	s_nop 0
	s_nop 0
	s_nop 0
	s_nop 0
	s_nop 0
	s_nop 0
	s_nop 0
	s_nop 0
	s_nop 0
	s_nop 0
	s_nop 0
	s_nop 0
	s_nop 0
	s_nop 0
	s_nop 0
	s_nop 0
	s_nop 0
	s_nop 0
	s_nop 0
	s_nop 0
	s_nop 0
	s_nop 0
	s_nop 0
	s_nop 0
	s_nop 0
	s_nop 0
	s_nop 0
	s_nop 0
	s_nop 0
	s_nop 0
	s_nop 0
	s_nop 0
	s_nop 0
	s_nop 0
	s_nop 0
	s_nop 0
	s_nop 0
	s_nop 0
	s_nop 0
	s_nop 0
	s_nop 0
	s_nop 0
	s_nop 0
	s_nop 0
	s_nop 0
	s_nop 0
	s_nop 0
	s_nop 0
	s_nop 0
	s_nop 0
	s_nop 0
	s_nop 0
	s_nop 0
	s_nop 0
	s_nop 0
	s_nop 0
	s_nop 0
	s_nop 0
	s_nop 0
	s_nop 0
	s_nop 0
	s_nop 0
	s_nop 0
	s_nop 0
	s_nop 0
	s_nop 0
	s_nop 0
	s_nop 0
	s_nop 0
	s_nop 0
	s_nop 0
	s_nop 0
	s_nop 0
	s_nop 0
	s_nop 0
	s_nop 0
	s_nop 0
	s_nop 0
	s_nop 0
	s_nop 0
	s_nop 0
	s_nop 0
	s_nop 0
	s_nop 0
	s_nop 0
	s_nop 0
	s_nop 0
	s_nop 0
	s_nop 0
	s_nop 0
	s_nop 0
	s_nop 0
	s_nop 0
	s_nop 0
	s_nop 0
	s_nop 0
	s_nop 0
	s_nop 0
	s_nop 0
	s_nop 0
	s_nop 0
	s_nop 0
	s_nop 0
	s_nop 0
	s_nop 0
	s_nop 0
	s_nop 0
	s_nop 0
	s_nop 0
	s_nop 0
	s_nop 0
	s_nop 0
	s_nop 0
	s_nop 0
	s_nop 0
	s_nop 0
	s_nop 0
	s_nop 0
	s_nop 0
	s_nop 0
	s_nop 0
	s_nop 0
	s_nop 0
	s_nop 0
	s_nop 0
	s_nop 0
	s_nop 0
	s_nop 0
	s_nop 0
	s_nop 0
	s_nop 0
	s_nop 0
	s_nop 0
	s_nop 0
	s_nop 0
	s_nop 0
	s_nop 0
	s_nop 0
	s_nop 0
	s_nop 0
	s_nop 0
	s_nop 0
	s_nop 0
	s_nop 0
	s_nop 0
	s_nop 0
	s_nop 0
	s_nop 0
	s_nop 0
	s_nop 0
	s_nop 0
	s_nop 0
	s_nop 0
	s_nop 0
	s_nop 0
	s_nop 0
	s_nop 0
	s_nop 0
	s_nop 0
	s_nop 0
	s_nop 0
	s_nop 0
	s_nop 0
	s_nop 0
	s_nop 0
	s_nop 0
	s_nop 0
	s_nop 0
	s_nop 0
	s_nop 0
	s_nop 0
	s_nop 0
	s_nop 0
	s_nop 0
	s_nop 0
	s_nop 0
	s_nop 0
	s_nop 0
	s_nop 0
	s_nop 0
	s_nop 0
	s_nop 0
	s_nop 0
	s_nop 0
	s_nop 0
	s_nop 0
	s_nop 0
	s_nop 0
	s_nop 0
	s_nop 0
	s_nop 0
	s_nop 0
	s_nop 0
	s_nop 0
	s_nop 0
	s_nop 0
	s_nop 0
	s_nop 0
	s_nop 0
	s_nop 0
	s_nop 0
	s_nop 0
	s_nop 0
	s_nop 0
	s_nop 0
	s_nop 0
	s_nop 0
	s_nop 0
	s_nop 0
	s_nop 0
	s_nop 0
	s_nop 0
	s_nop 0
	s_nop 0
	s_nop 0
	s_nop 0
	s_nop 0
	s_nop 0
	s_nop 0
	s_nop 0
	s_nop 0
	s_nop 0
	s_nop 0
	s_nop 0
	s_nop 0
	s_nop 0
	s_nop 0
	s_nop 0
	s_nop 0
	s_nop 0
	s_nop 0
	s_nop 0
	s_nop 0
	s_nop 0
	s_nop 0
	s_nop 0
	s_nop 0
	s_nop 0
	s_nop 0
	s_nop 0
	s_nop 0
	s_nop 0
	s_nop 0
	s_nop 0
	s_nop 0
	s_nop 0
	s_nop 0
	s_nop 0
	s_nop 0
	s_nop 0
	s_nop 0
	s_nop 0
	s_nop 0
	s_nop 0
	s_nop 0
	s_nop 0
	s_nop 0
	s_nop 0
	s_nop 0
	s_nop 0
	s_nop 0
	s_nop 0
	s_nop 0
	s_nop 0
	s_nop 0
	s_nop 0
	s_nop 0
	s_nop 0
	s_nop 0
	s_nop 0
	s_nop 0
	s_nop 0
	s_nop 0
	s_nop 0
	s_nop 0
	s_nop 0
	s_nop 0
	s_nop 0
	s_nop 0
	s_nop 0
	s_nop 0
	s_nop 0
	s_nop 0
	s_nop 0
	s_nop 0
	s_nop 0
	s_nop 0
	s_nop 0
	s_nop 0
	s_nop 0
	s_nop 0
	s_nop 0
	s_nop 0
	s_nop 0
	s_nop 0
	s_nop 0
	s_nop 0
	s_nop 0
	s_nop 0
	s_nop 0
	s_nop 0
	s_nop 0
	s_nop 0
	s_nop 0
	s_nop 0
	s_nop 0
	s_nop 0
	s_nop 0
	s_nop 0
	s_nop 0
	s_nop 0
	s_nop 0
	s_nop 0
	s_nop 0
	s_nop 0
	s_nop 0
	s_nop 0
	s_nop 0
	s_nop 0
	s_nop 0
	s_nop 0
	s_nop 0
	s_nop 0
	s_nop 0
	s_nop 0
	s_nop 0
	s_nop 0
.Lp0_done:
	s_nop 1
